# phase 8 rebalanced from 4/2 to 3/3 tiles per workgroup: the G2 second unit of tiles >= 256 runs on workgroup c+128; the single cross-workgroup dependency uses a release (L2 write-back + sc1 flag) afte
# speedup vs baseline: 1.0049x; 1.0049x over previous
.LBB0_1548:
	s_add_i32 s0, s0, 1
	s_waitcnt vmcnt(0)
	s_barrier
	s_cmp_eq_u32 s0, 5
	s_cbranch_scc0 .Lmy_p8_nosig
	s_cmp_lt_u32 s74, 0x80
	s_cbranch_scc0 .Lmy_p8_nosig
	v_cmp_eq_u32_e32 vcc, 0, v202
	s_and_saveexec_b64 s[98:99], vcc
	s_cbranch_execz .Lmy_p8_sigdone
	buffer_wbl2 sc1
	s_waitcnt vmcnt(0)
	v_readlane_b32 s100, v253, 2
	v_readlane_b32 s101, v253, 3
	s_lshl_b32 s4, s74, 2
	s_add_i32 s4, s4, 0x80000
	v_mov_b32_e32 v242, s4
	v_mov_b32_e32 v243, 1
	s_nop 4
	global_store_dword v242, v243, s[100:101] sc1
	s_waitcnt vmcnt(0)
.Lmy_p8_sigdone:
	s_or_b64 exec, exec, s[98:99]
.Lmy_p8_nosig:
	s_cmp_lt_u32 s0, s24
	s_cbranch_scc0 .LBB0_1439

.LBB0_1607:
	s_add_i32 s26, s26, 1
	s_mul_i32 s4, s26, s41
	s_mul_hi_u32 s5, s26, s78
	s_add_i32 s5, s5, s4
	s_mul_i32 s4, s26, s78
	s_add_u32 s4, s4, s33
	s_addc_u32 s5, s5, s91
	s_cmp_lg_u32 s66, 4
	s_cbranch_scc1 .Lmy_p8_map_done
	s_movk_i32 s98, 0x80
	s_cmp_lt_i32 s33, 0x80
	s_cbranch_scc1 .Lmy_p8_pos
	s_movk_i32 s98, 0xff80
.Lmy_p8_pos:
	s_ashr_i32 s99, s98, 31
	s_add_u32 s4, s4, s98
	s_addc_u32 s5, s5, s99
.Lmy_p8_map_done:
	v_mov_b64_e32 v[0:1], s[44:45]
	v_cmp_ge_i64_e32 vcc, s[4:5], v[0:1]
	v_cmp_lt_i64_e64 s[6:7], s[4:5], v[0:1]
	s_cbranch_vccnz .LBB0_1613
	s_ashr_i32 s5, s4, 31
	s_lshr_b32 s5, s5, 29
	s_add_i32 s17, s4, s5
	s_and_b32 s5, s17, -8
	s_sub_i32 s18, s4, s5
	s_cmp_ge_i32 s18, s16
	s_mov_b64 s[4:5], -1
	s_cbranch_scc0 .LBB0_1610
	s_sub_i32 s4, s18, s16
	s_mul_i32 s4, s4, s52
	s_mul_i32 s5, s1, s16
	s_add_i32 s19, s4, s5
	s_mov_b64 s[4:5], 0

.LBB0_1632:
	s_andn2_b64 vcc, exec, s[6:7]
	s_cbranch_vccnz .LBB0_1634
	s_cmp_eq_u32 s26, 2
	s_cbranch_scc0 .Lmy_p8_nowait
	v_cmp_eq_u32_e32 vcc, 0, v202
	s_and_saveexec_b64 s[98:99], vcc
	s_cbranch_execz .Lmy_p8_waited
	v_readlane_b32 s100, v253, 2
	v_readlane_b32 s101, v253, 3
	s_sub_i32 s6, s74, 0x80
	s_lshl_b32 s6, s6, 2
	s_add_i32 s6, s6, 0x80000
	v_mov_b32_e32 v242, s6
	s_mov_b32 s7, 0x100000
	s_nop 4
.Lmy_p8_poll:
	global_load_dword v243, v242, s[100:101] sc1
	s_waitcnt vmcnt(0)
	v_cmp_ne_u32_e32 vcc, 0, v243
	s_cbranch_vccnz .Lmy_p8_pollok
	s_sleep 1
	s_sub_u32 s7, s7, 1
	s_cmp_lg_u32 s7, 0
	s_cbranch_scc1 .Lmy_p8_poll

.Lmy_p8_waited:
	s_or_b64 exec, exec, s[98:99]
	s_barrier
.Lmy_p8_nowait:
	s_lshl_b32 s6, s83, 8
	v_readlane_b32 s8, v253, 2
	v_readlane_b32 s9, v253, 3
	v_add_u32_e32 v130, s6, v161
	v_lshl_or_b32 v128, s82, 8, v168
	v_ashrrev_i32_e32 v129, 31, v128
	v_lshlrev_b64 v[128:129], 1, v[128:129]
	v_mov_b32_e32 v132, v130
	v_ashrrev_i32_e32 v133, 31, v132
	v_lshlrev_b64 v[134:135], 12, v[132:133]
	v_lshl_add_u64 v[134:135], s[8:9], 0, v[134:135]
	v_lshl_add_u64 v[134:135], v[134:135], 0, s[58:59]
	v_lshl_add_u64 v[134:135], v[134:135], 0, v[128:129]
	global_load_dwordx4 v[170:173], v[134:135], off
	v_lshlrev_b64 v[134:135], 11, v[132:133]
	v_lshl_add_u64 v[134:135], s[46:47], 0, v[134:135]
	v_lshl_add_u64 v[134:135], v[134:135], 0, v[128:129]
	global_load_dwordx4 v[220:223], v[134:135], off
	v_mov_b32_e32 v132, v130
	v_ashrrev_i32_e32 v133, 31, v132
	v_lshlrev_b64 v[134:135], 12, v[132:133]
	v_lshl_add_u64 v[134:135], s[8:9], 0, v[134:135]
	v_lshl_add_u64 v[134:135], v[134:135], 0, s[58:59]
	v_lshl_add_u64 v[134:135], v[134:135], 0, v[128:129]
	global_load_dwordx4 v[188:191], v[134:135], off offset:256
	v_lshlrev_b64 v[134:135], 11, v[132:133]
	v_lshl_add_u64 v[134:135], s[46:47], 0, v[134:135]
	v_lshl_add_u64 v[134:135], v[134:135], 0, v[128:129]
	global_load_dwordx4 v[224:227], v[134:135], off offset:256
	v_or_b32_e32 v132, 16, v130
	v_ashrrev_i32_e32 v133, 31, v132
	v_lshlrev_b64 v[134:135], 12, v[132:133]
	v_lshl_add_u64 v[134:135], s[8:9], 0, v[134:135]
	v_lshl_add_u64 v[134:135], v[134:135], 0, s[58:59]
	v_lshl_add_u64 v[134:135], v[134:135], 0, v[128:129]
	global_load_dwordx4 v[192:195], v[134:135], off
	v_lshlrev_b64 v[134:135], 11, v[132:133]
	v_lshl_add_u64 v[134:135], s[46:47], 0, v[134:135]
	v_lshl_add_u64 v[134:135], v[134:135], 0, v[128:129]
	global_load_dwordx4 v[228:231], v[134:135], off
	v_or_b32_e32 v132, 16, v130
	v_ashrrev_i32_e32 v133, 31, v132
	v_lshlrev_b64 v[134:135], 12, v[132:133]
	v_lshl_add_u64 v[134:135], s[8:9], 0, v[134:135]
	v_lshl_add_u64 v[134:135], v[134:135], 0, s[58:59]
	v_lshl_add_u64 v[134:135], v[134:135], 0, v[128:129]
	global_load_dwordx4 v[196:199], v[134:135], off offset:256
	v_lshlrev_b64 v[134:135], 11, v[132:133]
	v_lshl_add_u64 v[134:135], s[46:47], 0, v[134:135]
	v_lshl_add_u64 v[134:135], v[134:135], 0, v[128:129]
	global_load_dwordx4 v[232:235], v[134:135], off offset:256
	v_or_b32_e32 v132, 32, v130
	v_ashrrev_i32_e32 v133, 31, v132
	v_lshlrev_b64 v[134:135], 12, v[132:133]
	v_lshl_add_u64 v[134:135], s[8:9], 0, v[134:135]
	v_lshl_add_u64 v[134:135], v[134:135], 0, s[58:59]
	v_lshl_add_u64 v[134:135], v[134:135], 0, v[128:129]
	global_load_dwordx4 v[204:207], v[134:135], off
	v_lshlrev_b64 v[134:135], 11, v[132:133]
	v_lshl_add_u64 v[134:135], s[46:47], 0, v[134:135]
	v_lshl_add_u64 v[134:135], v[134:135], 0, v[128:129]
	global_load_dwordx4 v[236:239], v[134:135], off
	v_or_b32_e32 v132, 32, v130
	v_ashrrev_i32_e32 v133, 31, v132
	v_lshlrev_b64 v[134:135], 12, v[132:133]
	v_lshl_add_u64 v[134:135], s[8:9], 0, v[134:135]
	v_lshl_add_u64 v[134:135], v[134:135], 0, s[58:59]
	v_lshl_add_u64 v[134:135], v[134:135], 0, v[128:129]
	global_load_dwordx4 v[208:211], v[134:135], off offset:256
	v_lshlrev_b64 v[134:135], 11, v[132:133]
	v_lshl_add_u64 v[134:135], s[46:47], 0, v[134:135]
	v_lshl_add_u64 v[134:135], v[134:135], 0, v[128:129]
	global_load_dwordx4 v[240:243], v[134:135], off offset:256
	v_or_b32_e32 v132, 48, v130
	v_ashrrev_i32_e32 v133, 31, v132
	v_lshlrev_b64 v[134:135], 12, v[132:133]
	v_lshl_add_u64 v[134:135], s[8:9], 0, v[134:135]
	v_lshl_add_u64 v[134:135], v[134:135], 0, s[58:59]
	v_lshl_add_u64 v[134:135], v[134:135], 0, v[128:129]
	global_load_dwordx4 v[212:215], v[134:135], off
	v_lshlrev_b64 v[134:135], 11, v[132:133]
	v_lshl_add_u64 v[134:135], s[46:47], 0, v[134:135]
	v_lshl_add_u64 v[134:135], v[134:135], 0, v[128:129]
	global_load_dwordx4 v[150:153], v[134:135], off
	v_or_b32_e32 v132, 48, v130
	v_ashrrev_i32_e32 v133, 31, v132
	v_lshlrev_b64 v[134:135], 12, v[132:133]
	v_lshl_add_u64 v[134:135], s[8:9], 0, v[134:135]
	v_lshl_add_u64 v[134:135], v[134:135], 0, s[58:59]
	v_lshl_add_u64 v[134:135], v[134:135], 0, v[128:129]
	global_load_dwordx4 v[216:219], v[134:135], off offset:256
	v_lshlrev_b64 v[134:135], 11, v[132:133]
	v_lshl_add_u64 v[134:135], s[46:47], 0, v[134:135]
	v_lshl_add_u64 v[134:135], v[134:135], 0, v[128:129]
	global_load_dwordx4 v[154:157], v[134:135], off offset:256
	v_mov_b32_e32 v132, v130
	v_ashrrev_i32_e32 v133, 31, v132
	v_lshlrev_b64 v[158:159], 11, v[132:133]
	v_lshl_add_u64 v[158:159], s[46:47], 0, v[158:159]
	v_lshl_add_u64 v[158:159], v[158:159], 0, v[128:129]
	s_waitcnt vmcnt(14)
	v_lshlrev_b32_e32 v200, 16, v220
	v_lshlrev_b32_e32 v136, 16, v170
	v_fmac_f32_e32 v200, v124, v136
	v_and_b32_e32 v220, 0xffff0000, v220
	v_and_b32_e32 v170, 0xffff0000, v170
	v_fmac_f32_e32 v220, v125, v170
	v_lshlrev_b32_e32 v201, 16, v221
	v_lshlrev_b32_e32 v136, 16, v171
	v_fmac_f32_e32 v201, v126, v136
	v_and_b32_e32 v221, 0xffff0000, v221
	v_and_b32_e32 v171, 0xffff0000, v171
	v_fmac_f32_e32 v221, v127, v171
	v_lshlrev_b32_e32 v244, 16, v222
	v_lshlrev_b32_e32 v136, 16, v172
	v_fmac_f32_e32 v244, v120, v136
	v_and_b32_e32 v222, 0xffff0000, v222
	v_and_b32_e32 v172, 0xffff0000, v172
	v_fmac_f32_e32 v222, v121, v172
	v_lshlrev_b32_e32 v245, 16, v223
	v_lshlrev_b32_e32 v136, 16, v173
	v_fmac_f32_e32 v245, v122, v136
	v_and_b32_e32 v223, 0xffff0000, v223
	v_and_b32_e32 v173, 0xffff0000, v173
	v_fmac_f32_e32 v223, v123, v173
	v_cvt_pk_bf16_f32 v220, v200, v220
	v_cvt_pk_bf16_f32 v221, v201, v221
	v_cvt_pk_bf16_f32 v222, v244, v222
	v_cvt_pk_bf16_f32 v223, v245, v223
	global_store_dwordx4 v[158:159], v[220:223], off
	v_add_u32_e32 v132, s6, v164
	v_ashrrev_i32_e32 v133, 31, v132
	v_lshlrev_b64 v[134:135], 12, v[132:133]
	v_lshl_add_u64 v[134:135], s[8:9], 0, v[134:135]
	v_lshl_add_u64 v[134:135], v[134:135], 0, s[58:59]
	v_lshl_add_u64 v[134:135], v[134:135], 0, v[128:129]
	global_load_dwordx4 v[170:173], v[134:135], off
	v_lshlrev_b64 v[134:135], 11, v[132:133]
	v_lshl_add_u64 v[134:135], s[46:47], 0, v[134:135]
	v_lshl_add_u64 v[134:135], v[134:135], 0, v[128:129]
	global_load_dwordx4 v[220:223], v[134:135], off
	v_mov_b32_e32 v132, v130
	v_ashrrev_i32_e32 v133, 31, v132
	v_lshlrev_b64 v[158:159], 11, v[132:133]
	v_lshl_add_u64 v[158:159], s[46:47], 0, v[158:159]
	v_lshl_add_u64 v[158:159], v[158:159], 0, v[128:129]
	s_waitcnt vmcnt(15)
	v_lshlrev_b32_e32 v200, 16, v224
	v_lshlrev_b32_e32 v136, 16, v188
	v_fmac_f32_e32 v200, v116, v136
	v_and_b32_e32 v224, 0xffff0000, v224
	v_and_b32_e32 v188, 0xffff0000, v188
	v_fmac_f32_e32 v224, v117, v188
	v_lshlrev_b32_e32 v201, 16, v225
	v_lshlrev_b32_e32 v136, 16, v189
	v_fmac_f32_e32 v201, v118, v136
	v_and_b32_e32 v225, 0xffff0000, v225
	v_and_b32_e32 v189, 0xffff0000, v189
	v_fmac_f32_e32 v225, v119, v189
	v_lshlrev_b32_e32 v244, 16, v226
	v_lshlrev_b32_e32 v136, 16, v190
	v_fmac_f32_e32 v244, v112, v136
	v_and_b32_e32 v226, 0xffff0000, v226
	v_and_b32_e32 v190, 0xffff0000, v190
	v_fmac_f32_e32 v226, v113, v190
	v_lshlrev_b32_e32 v245, 16, v227
	v_lshlrev_b32_e32 v136, 16, v191
	v_fmac_f32_e32 v245, v114, v136
	v_and_b32_e32 v227, 0xffff0000, v227
	v_and_b32_e32 v191, 0xffff0000, v191
	v_fmac_f32_e32 v227, v115, v191
	v_cvt_pk_bf16_f32 v224, v200, v224
	v_cvt_pk_bf16_f32 v225, v201, v225
	v_cvt_pk_bf16_f32 v226, v244, v226
	v_cvt_pk_bf16_f32 v227, v245, v227
	global_store_dwordx4 v[158:159], v[224:227], off offset:256
	v_add_u32_e32 v132, s6, v164
	v_ashrrev_i32_e32 v133, 31, v132
	v_lshlrev_b64 v[134:135], 12, v[132:133]
	v_lshl_add_u64 v[134:135], s[8:9], 0, v[134:135]
	v_lshl_add_u64 v[134:135], v[134:135], 0, s[58:59]
	v_lshl_add_u64 v[134:135], v[134:135], 0, v[128:129]
	global_load_dwordx4 v[188:191], v[134:135], off offset:256
	v_lshlrev_b64 v[134:135], 11, v[132:133]
	v_lshl_add_u64 v[134:135], s[46:47], 0, v[134:135]
	v_lshl_add_u64 v[134:135], v[134:135], 0, v[128:129]
	global_load_dwordx4 v[224:227], v[134:135], off offset:256
	v_or_b32_e32 v132, 16, v130
	v_ashrrev_i32_e32 v133, 31, v132
	v_lshlrev_b64 v[158:159], 11, v[132:133]
	v_lshl_add_u64 v[158:159], s[46:47], 0, v[158:159]
	v_lshl_add_u64 v[158:159], v[158:159], 0, v[128:129]
	s_waitcnt vmcnt(16)
	v_lshlrev_b32_e32 v200, 16, v228
	v_lshlrev_b32_e32 v136, 16, v192
	v_fmac_f32_e32 v200, v108, v136
	v_and_b32_e32 v228, 0xffff0000, v228
	v_and_b32_e32 v192, 0xffff0000, v192
	v_fmac_f32_e32 v228, v109, v192
	v_lshlrev_b32_e32 v201, 16, v229
	v_lshlrev_b32_e32 v136, 16, v193
	v_fmac_f32_e32 v201, v110, v136
	v_and_b32_e32 v229, 0xffff0000, v229
	v_and_b32_e32 v193, 0xffff0000, v193
	v_fmac_f32_e32 v229, v111, v193
	v_lshlrev_b32_e32 v244, 16, v230
	v_lshlrev_b32_e32 v136, 16, v194
	v_fmac_f32_e32 v244, v104, v136
	v_and_b32_e32 v230, 0xffff0000, v230
	v_and_b32_e32 v194, 0xffff0000, v194
	v_fmac_f32_e32 v230, v105, v194
	v_lshlrev_b32_e32 v245, 16, v231
	v_lshlrev_b32_e32 v136, 16, v195
	v_fmac_f32_e32 v245, v106, v136
	v_and_b32_e32 v231, 0xffff0000, v231
	v_and_b32_e32 v195, 0xffff0000, v195
	v_fmac_f32_e32 v231, v107, v195
	v_cvt_pk_bf16_f32 v228, v200, v228
	v_cvt_pk_bf16_f32 v229, v201, v229
	v_cvt_pk_bf16_f32 v230, v244, v230
	v_cvt_pk_bf16_f32 v231, v245, v231
	global_store_dwordx4 v[158:159], v[228:231], off
	v_add_u32_e32 v132, s6, v165
	v_ashrrev_i32_e32 v133, 31, v132
	v_lshlrev_b64 v[134:135], 12, v[132:133]
	v_lshl_add_u64 v[134:135], s[8:9], 0, v[134:135]
	v_lshl_add_u64 v[134:135], v[134:135], 0, s[58:59]
	v_lshl_add_u64 v[134:135], v[134:135], 0, v[128:129]
	global_load_dwordx4 v[192:195], v[134:135], off
	v_lshlrev_b64 v[134:135], 11, v[132:133]
	v_lshl_add_u64 v[134:135], s[46:47], 0, v[134:135]
	v_lshl_add_u64 v[134:135], v[134:135], 0, v[128:129]
	global_load_dwordx4 v[228:231], v[134:135], off
	v_or_b32_e32 v132, 16, v130
	v_ashrrev_i32_e32 v133, 31, v132
	v_lshlrev_b64 v[158:159], 11, v[132:133]
	v_lshl_add_u64 v[158:159], s[46:47], 0, v[158:159]
	v_lshl_add_u64 v[158:159], v[158:159], 0, v[128:129]
	s_waitcnt vmcnt(17)
	v_lshlrev_b32_e32 v200, 16, v232
	v_lshlrev_b32_e32 v136, 16, v196
	v_fmac_f32_e32 v200, v100, v136
	v_and_b32_e32 v232, 0xffff0000, v232
	v_and_b32_e32 v196, 0xffff0000, v196
	v_fmac_f32_e32 v232, v101, v196
	v_lshlrev_b32_e32 v201, 16, v233
	v_lshlrev_b32_e32 v136, 16, v197
	v_fmac_f32_e32 v201, v102, v136
	v_and_b32_e32 v233, 0xffff0000, v233
	v_and_b32_e32 v197, 0xffff0000, v197
	v_fmac_f32_e32 v233, v103, v197
	v_lshlrev_b32_e32 v244, 16, v234
	v_lshlrev_b32_e32 v136, 16, v198
	v_fmac_f32_e32 v244, v96, v136
	v_and_b32_e32 v234, 0xffff0000, v234
	v_and_b32_e32 v198, 0xffff0000, v198
	v_fmac_f32_e32 v234, v97, v198
	v_lshlrev_b32_e32 v245, 16, v235
	v_lshlrev_b32_e32 v136, 16, v199
	v_fmac_f32_e32 v245, v98, v136
	v_and_b32_e32 v235, 0xffff0000, v235
	v_and_b32_e32 v199, 0xffff0000, v199
	v_fmac_f32_e32 v235, v99, v199
	v_cvt_pk_bf16_f32 v232, v200, v232
	v_cvt_pk_bf16_f32 v233, v201, v233
	v_cvt_pk_bf16_f32 v234, v244, v234
	v_cvt_pk_bf16_f32 v235, v245, v235
	global_store_dwordx4 v[158:159], v[232:235], off offset:256
	v_add_u32_e32 v132, s6, v165
	v_ashrrev_i32_e32 v133, 31, v132
	v_lshlrev_b64 v[134:135], 12, v[132:133]
	v_lshl_add_u64 v[134:135], s[8:9], 0, v[134:135]
	v_lshl_add_u64 v[134:135], v[134:135], 0, s[58:59]
	v_lshl_add_u64 v[134:135], v[134:135], 0, v[128:129]
	global_load_dwordx4 v[196:199], v[134:135], off offset:256
	v_lshlrev_b64 v[134:135], 11, v[132:133]
	v_lshl_add_u64 v[134:135], s[46:47], 0, v[134:135]
	v_lshl_add_u64 v[134:135], v[134:135], 0, v[128:129]
	global_load_dwordx4 v[232:235], v[134:135], off offset:256
	v_or_b32_e32 v132, 32, v130
	v_ashrrev_i32_e32 v133, 31, v132
	v_lshlrev_b64 v[158:159], 11, v[132:133]
	v_lshl_add_u64 v[158:159], s[46:47], 0, v[158:159]
	v_lshl_add_u64 v[158:159], v[158:159], 0, v[128:129]
	s_waitcnt vmcnt(18)
	v_lshlrev_b32_e32 v200, 16, v236
	v_lshlrev_b32_e32 v136, 16, v204
	v_fmac_f32_e32 v200, v92, v136
	v_and_b32_e32 v236, 0xffff0000, v236
	v_and_b32_e32 v204, 0xffff0000, v204
	v_fmac_f32_e32 v236, v93, v204
	v_lshlrev_b32_e32 v201, 16, v237
	v_lshlrev_b32_e32 v136, 16, v205
	v_fmac_f32_e32 v201, v94, v136
	v_and_b32_e32 v237, 0xffff0000, v237
	v_and_b32_e32 v205, 0xffff0000, v205
	v_fmac_f32_e32 v237, v95, v205
	v_lshlrev_b32_e32 v244, 16, v238
	v_lshlrev_b32_e32 v136, 16, v206
	v_fmac_f32_e32 v244, v88, v136
	v_and_b32_e32 v238, 0xffff0000, v238
	v_and_b32_e32 v206, 0xffff0000, v206
	v_fmac_f32_e32 v238, v89, v206
	v_lshlrev_b32_e32 v245, 16, v239
	v_lshlrev_b32_e32 v136, 16, v207
	v_fmac_f32_e32 v245, v90, v136
	v_and_b32_e32 v239, 0xffff0000, v239
	v_and_b32_e32 v207, 0xffff0000, v207
	v_fmac_f32_e32 v239, v91, v207
	v_cvt_pk_bf16_f32 v236, v200, v236
	v_cvt_pk_bf16_f32 v237, v201, v237
	v_cvt_pk_bf16_f32 v238, v244, v238
	v_cvt_pk_bf16_f32 v239, v245, v239
	global_store_dwordx4 v[158:159], v[236:239], off
	v_add_u32_e32 v132, s6, v166
	v_ashrrev_i32_e32 v133, 31, v132
	v_lshlrev_b64 v[134:135], 12, v[132:133]
	v_lshl_add_u64 v[134:135], s[8:9], 0, v[134:135]
	v_lshl_add_u64 v[134:135], v[134:135], 0, s[58:59]
	v_lshl_add_u64 v[134:135], v[134:135], 0, v[128:129]
	global_load_dwordx4 v[204:207], v[134:135], off
	v_lshlrev_b64 v[134:135], 11, v[132:133]
	v_lshl_add_u64 v[134:135], s[46:47], 0, v[134:135]
	v_lshl_add_u64 v[134:135], v[134:135], 0, v[128:129]
	global_load_dwordx4 v[236:239], v[134:135], off
	v_or_b32_e32 v132, 32, v130
	v_ashrrev_i32_e32 v133, 31, v132
	v_lshlrev_b64 v[158:159], 11, v[132:133]
	v_lshl_add_u64 v[158:159], s[46:47], 0, v[158:159]
	v_lshl_add_u64 v[158:159], v[158:159], 0, v[128:129]
	s_waitcnt vmcnt(19)
	v_lshlrev_b32_e32 v200, 16, v240
	v_lshlrev_b32_e32 v136, 16, v208
	v_fmac_f32_e32 v200, v84, v136
	v_and_b32_e32 v240, 0xffff0000, v240
	v_and_b32_e32 v208, 0xffff0000, v208
	v_fmac_f32_e32 v240, v85, v208
	v_lshlrev_b32_e32 v201, 16, v241
	v_lshlrev_b32_e32 v136, 16, v209
	v_fmac_f32_e32 v201, v86, v136
	v_and_b32_e32 v241, 0xffff0000, v241
	v_and_b32_e32 v209, 0xffff0000, v209
	v_fmac_f32_e32 v241, v87, v209
	v_lshlrev_b32_e32 v244, 16, v242
	v_lshlrev_b32_e32 v136, 16, v210
	v_fmac_f32_e32 v244, v80, v136
	v_and_b32_e32 v242, 0xffff0000, v242
	v_and_b32_e32 v210, 0xffff0000, v210
	v_fmac_f32_e32 v242, v81, v210
	v_lshlrev_b32_e32 v245, 16, v243
	v_lshlrev_b32_e32 v136, 16, v211
	v_fmac_f32_e32 v245, v82, v136
	v_and_b32_e32 v243, 0xffff0000, v243
	v_and_b32_e32 v211, 0xffff0000, v211
	v_fmac_f32_e32 v243, v83, v211
	v_cvt_pk_bf16_f32 v240, v200, v240
	v_cvt_pk_bf16_f32 v241, v201, v241
	v_cvt_pk_bf16_f32 v242, v244, v242
	v_cvt_pk_bf16_f32 v243, v245, v243
	global_store_dwordx4 v[158:159], v[240:243], off offset:256
	v_add_u32_e32 v132, s6, v166
	v_ashrrev_i32_e32 v133, 31, v132
	v_lshlrev_b64 v[134:135], 12, v[132:133]
	v_lshl_add_u64 v[134:135], s[8:9], 0, v[134:135]
	v_lshl_add_u64 v[134:135], v[134:135], 0, s[58:59]
	v_lshl_add_u64 v[134:135], v[134:135], 0, v[128:129]
	global_load_dwordx4 v[208:211], v[134:135], off offset:256
	v_lshlrev_b64 v[134:135], 11, v[132:133]
	v_lshl_add_u64 v[134:135], s[46:47], 0, v[134:135]
	v_lshl_add_u64 v[134:135], v[134:135], 0, v[128:129]
	global_load_dwordx4 v[240:243], v[134:135], off offset:256
	v_or_b32_e32 v132, 48, v130
	v_ashrrev_i32_e32 v133, 31, v132
	v_lshlrev_b64 v[158:159], 11, v[132:133]
	v_lshl_add_u64 v[158:159], s[46:47], 0, v[158:159]
	v_lshl_add_u64 v[158:159], v[158:159], 0, v[128:129]
	s_waitcnt vmcnt(20)
	v_lshlrev_b32_e32 v200, 16, v150
	v_lshlrev_b32_e32 v136, 16, v212
	v_fmac_f32_e32 v200, v76, v136
	v_and_b32_e32 v150, 0xffff0000, v150
	v_and_b32_e32 v212, 0xffff0000, v212
	v_fmac_f32_e32 v150, v77, v212
	v_lshlrev_b32_e32 v201, 16, v151
	v_lshlrev_b32_e32 v136, 16, v213
	v_fmac_f32_e32 v201, v78, v136
	v_and_b32_e32 v151, 0xffff0000, v151
	v_and_b32_e32 v213, 0xffff0000, v213
	v_fmac_f32_e32 v151, v79, v213
	v_lshlrev_b32_e32 v244, 16, v152
	v_lshlrev_b32_e32 v136, 16, v214
	v_fmac_f32_e32 v244, v72, v136
	v_and_b32_e32 v152, 0xffff0000, v152
	v_and_b32_e32 v214, 0xffff0000, v214
	v_fmac_f32_e32 v152, v73, v214
	v_lshlrev_b32_e32 v245, 16, v153
	v_lshlrev_b32_e32 v136, 16, v215
	v_fmac_f32_e32 v245, v74, v136
	v_and_b32_e32 v153, 0xffff0000, v153
	v_and_b32_e32 v215, 0xffff0000, v215
	v_fmac_f32_e32 v153, v75, v215
	v_cvt_pk_bf16_f32 v150, v200, v150
	v_cvt_pk_bf16_f32 v151, v201, v151
	v_cvt_pk_bf16_f32 v152, v244, v152
	v_cvt_pk_bf16_f32 v153, v245, v153
	global_store_dwordx4 v[158:159], v[150:153], off
	v_add_u32_e32 v132, s6, v167
	v_ashrrev_i32_e32 v133, 31, v132
	v_lshlrev_b64 v[134:135], 12, v[132:133]
	v_lshl_add_u64 v[134:135], s[8:9], 0, v[134:135]
	v_lshl_add_u64 v[134:135], v[134:135], 0, s[58:59]
	v_lshl_add_u64 v[134:135], v[134:135], 0, v[128:129]
	global_load_dwordx4 v[212:215], v[134:135], off
	v_lshlrev_b64 v[134:135], 11, v[132:133]
	v_lshl_add_u64 v[134:135], s[46:47], 0, v[134:135]
	v_lshl_add_u64 v[134:135], v[134:135], 0, v[128:129]
	global_load_dwordx4 v[150:153], v[134:135], off
	v_or_b32_e32 v132, 48, v130
	v_ashrrev_i32_e32 v133, 31, v132
	v_lshlrev_b64 v[158:159], 11, v[132:133]
	v_lshl_add_u64 v[158:159], s[46:47], 0, v[158:159]
	v_lshl_add_u64 v[158:159], v[158:159], 0, v[128:129]
	s_waitcnt vmcnt(21)
	v_lshlrev_b32_e32 v200, 16, v154
	v_lshlrev_b32_e32 v136, 16, v216
	v_fmac_f32_e32 v200, v68, v136
	v_and_b32_e32 v154, 0xffff0000, v154
	v_and_b32_e32 v216, 0xffff0000, v216
	v_fmac_f32_e32 v154, v69, v216
	v_lshlrev_b32_e32 v201, 16, v155
	v_lshlrev_b32_e32 v136, 16, v217
	v_fmac_f32_e32 v201, v70, v136
	v_and_b32_e32 v155, 0xffff0000, v155
	v_and_b32_e32 v217, 0xffff0000, v217
	v_fmac_f32_e32 v155, v71, v217
	v_lshlrev_b32_e32 v244, 16, v156
	v_lshlrev_b32_e32 v136, 16, v218
	v_fmac_f32_e32 v244, v64, v136
	v_and_b32_e32 v156, 0xffff0000, v156
	v_and_b32_e32 v218, 0xffff0000, v218
	v_fmac_f32_e32 v156, v65, v218
	v_lshlrev_b32_e32 v245, 16, v157
	v_lshlrev_b32_e32 v136, 16, v219
	v_fmac_f32_e32 v245, v66, v136
	v_and_b32_e32 v157, 0xffff0000, v157
	v_and_b32_e32 v219, 0xffff0000, v219
	v_fmac_f32_e32 v157, v67, v219
	v_cvt_pk_bf16_f32 v154, v200, v154
	v_cvt_pk_bf16_f32 v155, v201, v155
	v_cvt_pk_bf16_f32 v156, v244, v156
	v_cvt_pk_bf16_f32 v157, v245, v157
	global_store_dwordx4 v[158:159], v[154:157], off offset:256
	v_add_u32_e32 v132, s6, v167
	v_ashrrev_i32_e32 v133, 31, v132
	v_lshlrev_b64 v[134:135], 12, v[132:133]
	v_lshl_add_u64 v[134:135], s[8:9], 0, v[134:135]
	v_lshl_add_u64 v[134:135], v[134:135], 0, s[58:59]
	v_lshl_add_u64 v[134:135], v[134:135], 0, v[128:129]
	global_load_dwordx4 v[216:219], v[134:135], off offset:256
	v_lshlrev_b64 v[134:135], 11, v[132:133]
	v_lshl_add_u64 v[134:135], s[46:47], 0, v[134:135]
	v_lshl_add_u64 v[134:135], v[134:135], 0, v[128:129]
	global_load_dwordx4 v[154:157], v[134:135], off offset:256
	v_add_u32_e32 v132, s6, v164
	v_ashrrev_i32_e32 v133, 31, v132
	v_lshlrev_b64 v[158:159], 11, v[132:133]
	v_lshl_add_u64 v[158:159], s[46:47], 0, v[158:159]
	v_lshl_add_u64 v[158:159], v[158:159], 0, v[128:129]
	s_waitcnt vmcnt(21)
	v_lshlrev_b32_e32 v200, 16, v220
	v_lshlrev_b32_e32 v136, 16, v170
	v_fmac_f32_e32 v200, v60, v136
	v_and_b32_e32 v220, 0xffff0000, v220
	v_and_b32_e32 v170, 0xffff0000, v170
	v_fmac_f32_e32 v220, v61, v170
	v_lshlrev_b32_e32 v201, 16, v221
	v_lshlrev_b32_e32 v136, 16, v171
	v_fmac_f32_e32 v201, v62, v136
	v_and_b32_e32 v221, 0xffff0000, v221
	v_and_b32_e32 v171, 0xffff0000, v171
	v_fmac_f32_e32 v221, v63, v171
	v_lshlrev_b32_e32 v244, 16, v222
	v_lshlrev_b32_e32 v136, 16, v172
	v_fmac_f32_e32 v244, v56, v136
	v_and_b32_e32 v222, 0xffff0000, v222
	v_and_b32_e32 v172, 0xffff0000, v172
	v_fmac_f32_e32 v222, v57, v172
	v_lshlrev_b32_e32 v245, 16, v223
	v_lshlrev_b32_e32 v136, 16, v173
	v_fmac_f32_e32 v245, v58, v136
	v_and_b32_e32 v223, 0xffff0000, v223
	v_and_b32_e32 v173, 0xffff0000, v173
	v_fmac_f32_e32 v223, v59, v173
	v_cvt_pk_bf16_f32 v220, v200, v220
	v_cvt_pk_bf16_f32 v221, v201, v221
	v_cvt_pk_bf16_f32 v222, v244, v222
	v_cvt_pk_bf16_f32 v223, v245, v223
	global_store_dwordx4 v[158:159], v[220:223], off
	v_add_u32_e32 v132, s6, v164
	v_ashrrev_i32_e32 v133, 31, v132
	v_lshlrev_b64 v[158:159], 11, v[132:133]
	v_lshl_add_u64 v[158:159], s[46:47], 0, v[158:159]
	v_lshl_add_u64 v[158:159], v[158:159], 0, v[128:129]
	s_waitcnt vmcnt(19)
	v_lshlrev_b32_e32 v200, 16, v224
	v_lshlrev_b32_e32 v136, 16, v188
	v_fmac_f32_e32 v200, v52, v136
	v_and_b32_e32 v224, 0xffff0000, v224
	v_and_b32_e32 v188, 0xffff0000, v188
	v_fmac_f32_e32 v224, v53, v188
	v_lshlrev_b32_e32 v201, 16, v225
	v_lshlrev_b32_e32 v136, 16, v189
	v_fmac_f32_e32 v201, v54, v136
	v_and_b32_e32 v225, 0xffff0000, v225
	v_and_b32_e32 v189, 0xffff0000, v189
	v_fmac_f32_e32 v225, v55, v189
	v_lshlrev_b32_e32 v244, 16, v226
	v_lshlrev_b32_e32 v136, 16, v190
	v_fmac_f32_e32 v244, v48, v136
	v_and_b32_e32 v226, 0xffff0000, v226
	v_and_b32_e32 v190, 0xffff0000, v190
	v_fmac_f32_e32 v226, v49, v190
	v_lshlrev_b32_e32 v245, 16, v227
	v_lshlrev_b32_e32 v136, 16, v191
	v_fmac_f32_e32 v245, v50, v136
	v_and_b32_e32 v227, 0xffff0000, v227
	v_and_b32_e32 v191, 0xffff0000, v191
	v_fmac_f32_e32 v227, v51, v191
	v_cvt_pk_bf16_f32 v224, v200, v224
	v_cvt_pk_bf16_f32 v225, v201, v225
	v_cvt_pk_bf16_f32 v226, v244, v226
	v_cvt_pk_bf16_f32 v227, v245, v227
	global_store_dwordx4 v[158:159], v[224:227], off offset:256
	v_add_u32_e32 v132, s6, v165
	v_ashrrev_i32_e32 v133, 31, v132
	v_lshlrev_b64 v[158:159], 11, v[132:133]
	v_lshl_add_u64 v[158:159], s[46:47], 0, v[158:159]
	v_lshl_add_u64 v[158:159], v[158:159], 0, v[128:129]
	s_waitcnt vmcnt(17)
	v_lshlrev_b32_e32 v200, 16, v228
	v_lshlrev_b32_e32 v136, 16, v192
	v_fmac_f32_e32 v200, v44, v136
	v_and_b32_e32 v228, 0xffff0000, v228
	v_and_b32_e32 v192, 0xffff0000, v192
	v_fmac_f32_e32 v228, v45, v192
	v_lshlrev_b32_e32 v201, 16, v229
	v_lshlrev_b32_e32 v136, 16, v193
	v_fmac_f32_e32 v201, v46, v136
	v_and_b32_e32 v229, 0xffff0000, v229
	v_and_b32_e32 v193, 0xffff0000, v193
	v_fmac_f32_e32 v229, v47, v193
	v_lshlrev_b32_e32 v244, 16, v230
	v_lshlrev_b32_e32 v136, 16, v194
	v_fmac_f32_e32 v244, v40, v136
	v_and_b32_e32 v230, 0xffff0000, v230
	v_and_b32_e32 v194, 0xffff0000, v194
	v_fmac_f32_e32 v230, v41, v194
	v_lshlrev_b32_e32 v245, 16, v231
	v_lshlrev_b32_e32 v136, 16, v195
	v_fmac_f32_e32 v245, v42, v136
	v_and_b32_e32 v231, 0xffff0000, v231
	v_and_b32_e32 v195, 0xffff0000, v195
	v_fmac_f32_e32 v231, v43, v195
	v_cvt_pk_bf16_f32 v228, v200, v228
	v_cvt_pk_bf16_f32 v229, v201, v229
	v_cvt_pk_bf16_f32 v230, v244, v230
	v_cvt_pk_bf16_f32 v231, v245, v231
	global_store_dwordx4 v[158:159], v[228:231], off
	v_add_u32_e32 v132, s6, v165
	v_ashrrev_i32_e32 v133, 31, v132
	v_lshlrev_b64 v[158:159], 11, v[132:133]
	v_lshl_add_u64 v[158:159], s[46:47], 0, v[158:159]
	v_lshl_add_u64 v[158:159], v[158:159], 0, v[128:129]
	s_waitcnt vmcnt(15)
	v_lshlrev_b32_e32 v200, 16, v232
	v_lshlrev_b32_e32 v136, 16, v196
	v_fmac_f32_e32 v200, v36, v136
	v_and_b32_e32 v232, 0xffff0000, v232
	v_and_b32_e32 v196, 0xffff0000, v196
	v_fmac_f32_e32 v232, v37, v196
	v_lshlrev_b32_e32 v201, 16, v233
	v_lshlrev_b32_e32 v136, 16, v197
	v_fmac_f32_e32 v201, v38, v136
	v_and_b32_e32 v233, 0xffff0000, v233
	v_and_b32_e32 v197, 0xffff0000, v197
	v_fmac_f32_e32 v233, v39, v197
	v_lshlrev_b32_e32 v244, 16, v234
	v_lshlrev_b32_e32 v136, 16, v198
	v_fmac_f32_e32 v244, v32, v136
	v_and_b32_e32 v234, 0xffff0000, v234
	v_and_b32_e32 v198, 0xffff0000, v198
	v_fmac_f32_e32 v234, v33, v198
	v_lshlrev_b32_e32 v245, 16, v235
	v_lshlrev_b32_e32 v136, 16, v199
	v_fmac_f32_e32 v245, v34, v136
	v_and_b32_e32 v235, 0xffff0000, v235
	v_and_b32_e32 v199, 0xffff0000, v199
	v_fmac_f32_e32 v235, v35, v199
	v_cvt_pk_bf16_f32 v232, v200, v232
	v_cvt_pk_bf16_f32 v233, v201, v233
	v_cvt_pk_bf16_f32 v234, v244, v234
	v_cvt_pk_bf16_f32 v235, v245, v235
	global_store_dwordx4 v[158:159], v[232:235], off offset:256
	v_add_u32_e32 v132, s6, v166
	v_ashrrev_i32_e32 v133, 31, v132
	v_lshlrev_b64 v[158:159], 11, v[132:133]
	v_lshl_add_u64 v[158:159], s[46:47], 0, v[158:159]
	v_lshl_add_u64 v[158:159], v[158:159], 0, v[128:129]
	s_waitcnt vmcnt(13)
	v_lshlrev_b32_e32 v200, 16, v236
	v_lshlrev_b32_e32 v136, 16, v204
	v_fmac_f32_e32 v200, v28, v136
	v_and_b32_e32 v236, 0xffff0000, v236
	v_and_b32_e32 v204, 0xffff0000, v204
	v_fmac_f32_e32 v236, v29, v204
	v_lshlrev_b32_e32 v201, 16, v237
	v_lshlrev_b32_e32 v136, 16, v205
	v_fmac_f32_e32 v201, v30, v136
	v_and_b32_e32 v237, 0xffff0000, v237
	v_and_b32_e32 v205, 0xffff0000, v205
	v_fmac_f32_e32 v237, v31, v205
	v_lshlrev_b32_e32 v244, 16, v238
	v_lshlrev_b32_e32 v136, 16, v206
	v_fmac_f32_e32 v244, v24, v136
	v_and_b32_e32 v238, 0xffff0000, v238
	v_and_b32_e32 v206, 0xffff0000, v206
	v_fmac_f32_e32 v238, v25, v206
	v_lshlrev_b32_e32 v245, 16, v239
	v_lshlrev_b32_e32 v136, 16, v207
	v_fmac_f32_e32 v245, v26, v136
	v_and_b32_e32 v239, 0xffff0000, v239
	v_and_b32_e32 v207, 0xffff0000, v207
	v_fmac_f32_e32 v239, v27, v207
	v_cvt_pk_bf16_f32 v236, v200, v236
	v_cvt_pk_bf16_f32 v237, v201, v237
	v_cvt_pk_bf16_f32 v238, v244, v238
	v_cvt_pk_bf16_f32 v239, v245, v239
	global_store_dwordx4 v[158:159], v[236:239], off
	v_add_u32_e32 v132, s6, v166
	v_ashrrev_i32_e32 v133, 31, v132
	v_lshlrev_b64 v[158:159], 11, v[132:133]
	v_lshl_add_u64 v[158:159], s[46:47], 0, v[158:159]
	v_lshl_add_u64 v[158:159], v[158:159], 0, v[128:129]
	s_waitcnt vmcnt(11)
	v_lshlrev_b32_e32 v200, 16, v240
	v_lshlrev_b32_e32 v136, 16, v208
	v_fmac_f32_e32 v200, v20, v136
	v_and_b32_e32 v240, 0xffff0000, v240
	v_and_b32_e32 v208, 0xffff0000, v208
	v_fmac_f32_e32 v240, v21, v208
	v_lshlrev_b32_e32 v201, 16, v241
	v_lshlrev_b32_e32 v136, 16, v209
	v_fmac_f32_e32 v201, v22, v136
	v_and_b32_e32 v241, 0xffff0000, v241
	v_and_b32_e32 v209, 0xffff0000, v209
	v_fmac_f32_e32 v241, v23, v209
	v_lshlrev_b32_e32 v244, 16, v242
	v_lshlrev_b32_e32 v136, 16, v210
	v_fmac_f32_e32 v244, v16, v136
	v_and_b32_e32 v242, 0xffff0000, v242
	v_and_b32_e32 v210, 0xffff0000, v210
	v_fmac_f32_e32 v242, v17, v210
	v_lshlrev_b32_e32 v245, 16, v243
	v_lshlrev_b32_e32 v136, 16, v211
	v_fmac_f32_e32 v245, v18, v136
	v_and_b32_e32 v243, 0xffff0000, v243
	v_and_b32_e32 v211, 0xffff0000, v211
	v_fmac_f32_e32 v243, v19, v211
	v_cvt_pk_bf16_f32 v240, v200, v240
	v_cvt_pk_bf16_f32 v241, v201, v241
	v_cvt_pk_bf16_f32 v242, v244, v242
	v_cvt_pk_bf16_f32 v243, v245, v243
	global_store_dwordx4 v[158:159], v[240:243], off offset:256
	v_add_u32_e32 v132, s6, v167
	v_ashrrev_i32_e32 v133, 31, v132
	v_lshlrev_b64 v[158:159], 11, v[132:133]
	v_lshl_add_u64 v[158:159], s[46:47], 0, v[158:159]
	v_lshl_add_u64 v[158:159], v[158:159], 0, v[128:129]
	s_waitcnt vmcnt(9)
	v_lshlrev_b32_e32 v200, 16, v150
	v_lshlrev_b32_e32 v136, 16, v212
	v_fmac_f32_e32 v200, v12, v136
	v_and_b32_e32 v150, 0xffff0000, v150
	v_and_b32_e32 v212, 0xffff0000, v212
	v_fmac_f32_e32 v150, v13, v212
	v_lshlrev_b32_e32 v201, 16, v151
	v_lshlrev_b32_e32 v136, 16, v213
	v_fmac_f32_e32 v201, v14, v136
	v_and_b32_e32 v151, 0xffff0000, v151
	v_and_b32_e32 v213, 0xffff0000, v213
	v_fmac_f32_e32 v151, v15, v213
	v_lshlrev_b32_e32 v244, 16, v152
	v_lshlrev_b32_e32 v136, 16, v214
	v_fmac_f32_e32 v244, v8, v136
	v_and_b32_e32 v152, 0xffff0000, v152
	v_and_b32_e32 v214, 0xffff0000, v214
	v_fmac_f32_e32 v152, v9, v214
	v_lshlrev_b32_e32 v245, 16, v153
	v_lshlrev_b32_e32 v136, 16, v215
	v_fmac_f32_e32 v245, v10, v136
	v_and_b32_e32 v153, 0xffff0000, v153
	v_and_b32_e32 v215, 0xffff0000, v215
	v_fmac_f32_e32 v153, v11, v215
	v_cvt_pk_bf16_f32 v150, v200, v150
	v_cvt_pk_bf16_f32 v151, v201, v151
	v_cvt_pk_bf16_f32 v152, v244, v152
	v_cvt_pk_bf16_f32 v153, v245, v153
	global_store_dwordx4 v[158:159], v[150:153], off
	v_add_u32_e32 v132, s6, v167
	v_ashrrev_i32_e32 v133, 31, v132
	v_lshlrev_b64 v[158:159], 11, v[132:133]
	v_lshl_add_u64 v[158:159], s[46:47], 0, v[158:159]
	v_lshl_add_u64 v[158:159], v[158:159], 0, v[128:129]
	s_waitcnt vmcnt(7)
	v_lshlrev_b32_e32 v200, 16, v154
	v_lshlrev_b32_e32 v136, 16, v216
	v_fmac_f32_e32 v200, v4, v136
	v_and_b32_e32 v154, 0xffff0000, v154
	v_and_b32_e32 v216, 0xffff0000, v216
	v_fmac_f32_e32 v154, v5, v216
	v_lshlrev_b32_e32 v201, 16, v155
	v_lshlrev_b32_e32 v136, 16, v217
	v_fmac_f32_e32 v201, v6, v136
	v_and_b32_e32 v155, 0xffff0000, v155
	v_and_b32_e32 v217, 0xffff0000, v217
	v_fmac_f32_e32 v155, v7, v217
	v_lshlrev_b32_e32 v244, 16, v156
	v_lshlrev_b32_e32 v136, 16, v218
	v_fmac_f32_e32 v244, v0, v136
	v_and_b32_e32 v156, 0xffff0000, v156
	v_and_b32_e32 v218, 0xffff0000, v218
	v_fmac_f32_e32 v156, v1, v218
	v_lshlrev_b32_e32 v245, 16, v157
	v_lshlrev_b32_e32 v136, 16, v219
	v_fmac_f32_e32 v245, v2, v136
	v_and_b32_e32 v157, 0xffff0000, v157
	v_and_b32_e32 v219, 0xffff0000, v219
	v_fmac_f32_e32 v157, v3, v219
	v_cvt_pk_bf16_f32 v154, v200, v154
	v_cvt_pk_bf16_f32 v155, v201, v155
	v_cvt_pk_bf16_f32 v156, v244, v156
	v_cvt_pk_bf16_f32 v157, v245, v157
	global_store_dwordx4 v[158:159], v[154:157], off offset:256
	v_readlane_b32 s10, v253, 4
	v_readlane_b32 s11, v253, 5
